# cseq chunk loop: back-edge-counted vmcnt waits (no longer waiting for the 8 YB stores), preheader drain, batched S' LDS read-add-write
# speedup vs baseline: 1.0005x; 1.0005x over previous
.LBB0_620:
	s_or_b64 exec, exec, s[8:9]
	s_ashr_i32 s12, s56, 3
	s_and_b32 s24, s56, 7
	s_lshl_b32 s25, s12, 12
	s_lshl_b32 s8, s56, 6
	s_lshl_b32 s9, s24, 7
	s_add_u32 s10, s31, s9
	s_addc_u32 s11, s34, 0
	s_ashr_i32 s9, s8, 31
	s_lshl_b64 s[8:9], s[8:9], 13
	s_add_u32 s22, s35, s8
	s_addc_u32 s23, s36, s9
	v_ashrrev_i32_e32 v25, 4, v38
	v_ashrrev_i32_e32 v24, 3, v38
	s_add_u32 s26, s37, s8
	v_lshlrev_b32_e32 v10, 6, v25
	v_add_u32_e32 v44, s25, v25
	s_addc_u32 s27, s38, s9
	v_lshlrev_b32_e32 v0, 2, v38
	v_lshlrev_b32_e32 v2, 6, v24
	v_ashrrev_i32_e32 v11, 31, v10
	v_ashrrev_i32_e32 v45, 31, v44
	s_add_u32 s56, s39, s8
	v_and_b32_e32 v26, 60, v0
	v_ashrrev_i32_e32 v3, 31, v2
	v_lshlrev_b64 v[12:13], 1, v[10:11]
	v_add_u32_e32 v10, 0x800, v10
	v_lshlrev_b64 v[20:21], 10, v[44:45]
	s_addc_u32 s57, s40, s9
	v_lshlrev_b64 v[42:43], 1, v[2:3]
	v_lshlrev_b32_e32 v0, 4, v38
	v_lshlrev_b32_e32 v16, 1, v26
	v_mov_b32_e32 v17, v1
	v_ashrrev_i32_e32 v11, 31, v10
	v_lshl_add_u64 v[20:21], s[10:11], 0, v[20:21]
	v_lshl_add_u64 v[2:3], s[22:23], 0, v[42:43]
	v_and_b32_e32 v0, 0x70, v0
	v_lshl_add_u64 v[4:5], s[26:27], 0, v[42:43]
	v_lshl_add_u64 v[14:15], s[56:57], 0, v[12:13]
	v_lshlrev_b64 v[10:11], 1, v[10:11]
	v_lshl_add_u64 v[20:21], v[20:21], 0, v[16:17]
	v_lshl_add_u64 v[2:3], v[2:3], 0, v[0:1]
	s_waitcnt vmcnt(12)
	v_lshl_add_u64 v[6:7], v[4:5], 0, v[0:1]
	v_lshl_add_u64 v[14:15], v[14:15], 0, v[16:17]
	v_lshl_add_u64 v[18:19], s[56:57], 0, v[10:11]
	v_add_co_u32_e32 v22, vcc, s2, v20
	global_load_dwordx4 v[2:5], v[2:3], off
	s_nop 0
	global_load_dwordx4 v[6:9], v[6:7], off
	v_lshl_add_u64 v[18:19], v[18:19], 0, v[16:17]
	v_addc_co_u32_e32 v23, vcc, 0, v21, vcc
	global_load_dwordx2 v[48:49], v[14:15], off
	global_load_dwordx2 v[50:51], v[18:19], off
	global_load_dwordx2 v[52:53], v[20:21], off
	global_load_dwordx2 v[54:55], v[22:23], off
	s_movk_i32 s22, 0x90
	v_mul_lo_u32 v20, v24, s22
	v_bfe_u32 v15, v38, 4, 2
	v_add3_u32 v39, 0, v20, v0
	v_mul_lo_u32 v0, v25, s33
	v_lshlrev_b32_e32 v20, 2, v26
	v_and_b32_e32 v18, 15, v38
	v_and_b32_e32 v19, -16, v24
	v_lshrrev_b32_e32 v14, 1, v38
	v_add3_u32 v45, 0, v0, v20
	v_bfi_b32 v0, -16, v24, v38
	v_lshlrev_b32_e32 v21, 2, v15
	v_lshl_add_u64 v[46:47], s[10:11], 0, v[16:17]
	v_mul_lo_u32 v16, v0, s22
	v_and_or_b32 v14, v14, 32, v18
	v_or_b32_e32 v22, v21, v19
	s_movk_i32 s26, 0x44
	v_add_u32_e32 v20, 0, v16
	v_mad_u64_u32 v[16:17], s[22:23], v22, s26, v[14:15]
	v_lshlrev_b32_e32 v0, 7, v0
	v_lshlrev_b32_e32 v17, 4, v15
	v_lshlrev_b32_e32 v15, 5, v15
	v_add3_u32 v65, v20, v0, v15
	v_lshlrev_b32_e32 v0, 1, v14
	v_lshl_add_u64 v[56:57], s[10:11], 0, v[0:1]
	v_or_b32_e32 v0, 1, v22
	v_lshl_add_u32 v63, v16, 2, 0
	v_mul_u32_u24_e32 v16, 0x110, v14
	v_add_u32_e32 v64, v20, v17
	v_add_u32_e32 v20, 0, v15
	v_mul_u32_u24_e32 v23, 0x90, v14
	v_lshl_add_u32 v25, v14, 2, 0
	v_mad_u64_u32 v[14:15], s[10:11], v0, s26, v[14:15]
	v_add_u32_e32 v0, s25, v19
	v_or_b32_e32 v69, v0, v21
	v_mov_b32_e32 v0, 0x273fa000
	v_lshl_or_b32 v0, v18, 3, v0
	v_sub_u32_e32 v17, v20, v17
	v_mul_lo_u32 v24, v22, s33
	v_lshl_add_u32 v66, v14, 2, 0
	v_lshl_add_u64 v[58:59], v[0:1], 0, v[10:11]
	s_add_u32 s8, s14, s8
	v_lshl_add_u64 v[60:61], v[0:1], 0, v[12:13]
	v_and_b32_e32 v0, 7, v38
	s_mov_b32 s13, 0
	v_add_u32_e32 v62, 0x2200, v45
	v_add_u32_e32 v67, 0x110, v66
	v_add_u32_e32 v68, 0x220, v66
	s_addc_u32 s9, s15, s9
	v_lshl_or_b32 v42, v0, 4, v42
	v_add_u32_e32 v0, v20, v16
	v_add_u32_e32 v70, v17, v23
	v_add_u32_e32 v71, v25, v24
	s_mov_b32 s10, 0
	s_waitcnt vmcnt(0)
	s_branch .LBB0_622
.LBB0_621:
	ds_read_b128 v[10:13], v64 offset:52224
	ds_read_b128 v[14:17], v65
	ds_read_b128 v[18:21], v65 offset:16
	s_waitcnt lgkmcnt(1)
	v_cvt_pk_bf16_f32 v22, v14, v15
	v_lshlrev_b32_e32 v24, 16, v22
	v_and_b32_e32 v25, 0xffff0000, v22
	v_pk_add_f32 v[14:15], v[14:15], v[24:25] neg_lo:[0,1] neg_hi:[0,1]
	v_cvt_pk_bf16_f32 v23, v16, v17
	v_cvt_pk_bf16_f32 v26, v14, v15
	v_lshlrev_b32_e32 v14, 16, v23
	v_and_b32_e32 v15, 0xffff0000, v23
	v_pk_add_f32 v[14:15], v[16:17], v[14:15] neg_lo:[0,1] neg_hi:[0,1]
	s_waitcnt lgkmcnt(0)
	v_cvt_pk_bf16_f32 v24, v18, v19
	v_cvt_pk_bf16_f32 v27, v14, v15
	v_lshlrev_b32_e32 v14, 16, v24
	v_and_b32_e32 v15, 0xffff0000, v24
	v_pk_add_f32 v[14:15], v[18:19], v[14:15] neg_lo:[0,1] neg_hi:[0,1]
	v_cvt_pk_bf16_f32 v25, v20, v21
	v_cvt_pk_bf16_f32 v28, v14, v15
	v_lshlrev_b32_e32 v14, 16, v25
	v_and_b32_e32 v15, 0xffff0000, v25
	v_pk_add_f32 v[14:15], v[20:21], v[14:15] neg_lo:[0,1] neg_hi:[0,1]
	s_nop 0
	v_cvt_pk_bf16_f32 v29, v14, v15
	ds_read_b128 v[14:17], v0
	ds_read_b128 v[18:21], v0 offset:16
	s_waitcnt lgkmcnt(1)
	v_cvt_pk_bf16_f32 v30, v14, v15
	v_lshlrev_b32_e32 v32, 16, v30
	v_and_b32_e32 v33, 0xffff0000, v30
	v_cvt_pk_bf16_f32 v31, v16, v17
	v_pk_add_f32 v[14:15], v[14:15], v[32:33] neg_lo:[0,1] neg_hi:[0,1]
	v_lshlrev_b32_e32 v32, 16, v31
	v_and_b32_e32 v33, 0xffff0000, v31
	v_pk_add_f32 v[16:17], v[16:17], v[32:33] neg_lo:[0,1] neg_hi:[0,1]
	s_waitcnt lgkmcnt(0)
	v_cvt_pk_bf16_f32 v32, v18, v19
	v_cvt_pk_bf16_f32 v14, v14, v15
	v_cvt_pk_bf16_f32 v15, v16, v17
	v_lshlrev_b32_e32 v16, 16, v32
	v_and_b32_e32 v17, 0xffff0000, v32
	v_cvt_pk_bf16_f32 v33, v20, v21
	v_pk_add_f32 v[16:17], v[18:19], v[16:17] neg_lo:[0,1] neg_hi:[0,1]
	v_lshlrev_b32_e32 v18, 16, v33
	v_and_b32_e32 v19, 0xffff0000, v33
	v_pk_add_f32 v[18:19], v[20:21], v[18:19] neg_lo:[0,1] neg_hi:[0,1]
	v_cvt_pk_bf16_f32 v16, v16, v17
	v_cvt_pk_bf16_f32 v17, v18, v19
	v_mfma_f32_16x16x32_bf16 v[18:21], v[10:13], v[30:33], 0
	ds_read_b128 v[30:33], v0 offset:4368
	v_mfma_f32_16x16x32_bf16 v[72:75], v[10:13], v[14:17], v[18:21]
	ds_read_b128 v[14:17], v70 offset:61440
	s_waitcnt lgkmcnt(0)
	v_mfma_f32_16x16x32_bf16 v[18:21], v[22:25], v[14:17], 0
	v_mfma_f32_16x16x32_bf16 v[34:37], v[26:29], v[14:17], v[18:21]
	ds_read_b128 v[14:17], v0 offset:4352
	s_waitcnt lgkmcnt(0)
	s_nop 4
	v_cvt_pk_bf16_f32 v18, v14, v15
	v_lshlrev_b32_e32 v20, 16, v18
	v_and_b32_e32 v21, 0xffff0000, v18
	v_cvt_pk_bf16_f32 v19, v16, v17
	v_pk_add_f32 v[14:15], v[14:15], v[20:21] neg_lo:[0,1] neg_hi:[0,1]
	v_lshlrev_b32_e32 v20, 16, v19
	v_and_b32_e32 v21, 0xffff0000, v19
	v_pk_add_f32 v[16:17], v[16:17], v[20:21] neg_lo:[0,1] neg_hi:[0,1]
	v_cvt_pk_bf16_f32 v20, v30, v31
	v_cvt_pk_bf16_f32 v14, v14, v15
	v_cvt_pk_bf16_f32 v15, v16, v17
	v_lshlrev_b32_e32 v16, 16, v20
	v_and_b32_e32 v17, 0xffff0000, v20
	v_cvt_pk_bf16_f32 v21, v32, v33
	v_pk_add_f32 v[16:17], v[30:31], v[16:17] neg_lo:[0,1] neg_hi:[0,1]
	v_lshlrev_b32_e32 v30, 16, v21
	v_and_b32_e32 v31, 0xffff0000, v21
	v_mfma_f32_16x16x32_bf16 v[18:21], v[10:13], v[18:21], 0
	v_add_f32_e64 v30, v32, -v30
	v_add_f32_e64 v31, v33, -v31
	v_cvt_pk_bf16_f32 v16, v16, v17
	v_cvt_pk_bf16_f32 v17, v30, v31
	s_nop 1
	v_mfma_f32_16x16x32_bf16 v[14:17], v[10:13], v[14:17], v[18:21]
	ds_read_b128 v[10:13], v70 offset:63744
	s_waitcnt lgkmcnt(0)
	v_mfma_f32_16x16x32_bf16 v[18:21], v[22:25], v[10:13], 0
	v_mfma_f32_16x16x32_bf16 v[18:21], v[26:29], v[10:13], v[18:21]
	ds_read_b128 v[22:25], v64 offset:52288
	ds_read_b128 v[10:13], v65 offset:128
	s_waitcnt lgkmcnt(0)
	v_cvt_pk_bf16_f32 v26, v10, v11
	v_lshlrev_b32_e32 v28, 16, v26
	v_and_b32_e32 v29, 0xffff0000, v26
	v_pk_add_f32 v[10:11], v[10:11], v[28:29] neg_lo:[0,1] neg_hi:[0,1]
	v_cvt_pk_bf16_f32 v27, v12, v13
	v_cvt_pk_bf16_f32 v30, v10, v11
	v_lshlrev_b32_e32 v10, 16, v27
	v_and_b32_e32 v11, 0xffff0000, v27
	v_pk_add_f32 v[10:11], v[12:13], v[10:11] neg_lo:[0,1] neg_hi:[0,1]
	s_nop 0
	v_cvt_pk_bf16_f32 v31, v10, v11
	ds_read_b128 v[10:13], v65 offset:144
	s_waitcnt lgkmcnt(0)
	v_cvt_pk_bf16_f32 v28, v10, v11
	v_lshlrev_b32_e32 v32, 16, v28
	v_and_b32_e32 v33, 0xffff0000, v28
	v_pk_add_f32 v[10:11], v[10:11], v[32:33] neg_lo:[0,1] neg_hi:[0,1]
	v_cvt_pk_bf16_f32 v29, v12, v13
	v_cvt_pk_bf16_f32 v32, v10, v11
	v_lshlrev_b32_e32 v10, 16, v29
	v_and_b32_e32 v11, 0xffff0000, v29
	v_pk_add_f32 v[10:11], v[12:13], v[10:11] neg_lo:[0,1] neg_hi:[0,1]
	s_nop 0
	v_cvt_pk_bf16_f32 v33, v10, v11
	ds_read_b128 v[10:13], v0 offset:128
	ds_read_b128 v[76:79], v0 offset:144
	s_waitcnt lgkmcnt(1)
	v_cvt_pk_bf16_f32 v80, v10, v11
	v_lshlrev_b32_e32 v82, 16, v80
	v_and_b32_e32 v83, 0xffff0000, v80
	v_cvt_pk_bf16_f32 v81, v12, v13
	v_pk_add_f32 v[10:11], v[10:11], v[82:83] neg_lo:[0,1] neg_hi:[0,1]
	v_lshlrev_b32_e32 v82, 16, v81
	v_and_b32_e32 v83, 0xffff0000, v81
	v_pk_add_f32 v[12:13], v[12:13], v[82:83] neg_lo:[0,1] neg_hi:[0,1]
	s_waitcnt lgkmcnt(0)
	v_cvt_pk_bf16_f32 v82, v76, v77
	v_cvt_pk_bf16_f32 v83, v78, v79
	v_cvt_pk_bf16_f32 v10, v10, v11
	v_cvt_pk_bf16_f32 v11, v12, v13
	v_lshlrev_b32_e32 v12, 16, v82
	v_and_b32_e32 v13, 0xffff0000, v82
	v_mfma_f32_16x16x32_bf16 v[72:75], v[22:25], v[80:83], v[72:75]
	v_add_f32_e64 v12, v76, -v12
	v_add_f32_e64 v13, v77, -v13
	v_lshlrev_b32_e32 v76, 16, v83
	v_and_b32_e32 v77, 0xffff0000, v83
	v_pk_add_f32 v[76:77], v[78:79], v[76:77] neg_lo:[0,1] neg_hi:[0,1]
	v_cvt_pk_bf16_f32 v12, v12, v13
	v_cvt_pk_bf16_f32 v13, v76, v77
	ds_read_b128 v[80:83], v0 offset:4496
	s_nop 0
	v_mfma_f32_16x16x32_bf16 v[10:13], v[22:25], v[10:13], v[72:75]
	s_nop 2
	ds_read_b128 v[72:75], v70 offset:61504
	s_waitcnt lgkmcnt(0)
	v_mfma_f32_16x16x32_bf16 v[34:37], v[26:29], v[72:75], v[34:37]
	v_mfma_f32_16x16x32_bf16 v[34:37], v[30:33], v[72:75], v[34:37]
	ds_read_b128 v[72:75], v0 offset:4480
	s_waitcnt lgkmcnt(0)
	v_cvt_pk_bf16_f32 v76, v72, v73
	v_lshlrev_b32_e32 v78, 16, v76
	v_and_b32_e32 v79, 0xffff0000, v76
	v_cvt_pk_bf16_f32 v77, v74, v75
	v_pk_add_f32 v[72:73], v[72:73], v[78:79] neg_lo:[0,1] neg_hi:[0,1]
	v_lshlrev_b32_e32 v78, 16, v77
	v_and_b32_e32 v79, 0xffff0000, v77
	v_pk_add_f32 v[74:75], v[74:75], v[78:79] neg_lo:[0,1] neg_hi:[0,1]
	v_cvt_pk_bf16_f32 v78, v80, v81
	v_cvt_pk_bf16_f32 v79, v82, v83
	v_cvt_pk_bf16_f32 v72, v72, v73
	v_cvt_pk_bf16_f32 v73, v74, v75
	v_lshlrev_b32_e32 v74, 16, v78
	v_and_b32_e32 v75, 0xffff0000, v78
	v_mfma_f32_16x16x32_bf16 v[14:17], v[22:25], v[76:79], v[14:17]
	v_add_f32_e64 v74, v80, -v74
	v_add_f32_e64 v75, v81, -v75
	v_lshlrev_b32_e32 v80, 16, v79
	v_and_b32_e32 v81, 0xffff0000, v79
	v_pk_add_f32 v[80:81], v[82:83], v[80:81] neg_lo:[0,1] neg_hi:[0,1]
	v_cvt_pk_bf16_f32 v74, v74, v75
	v_cvt_pk_bf16_f32 v75, v80, v81
	s_nop 1
	v_mfma_f32_16x16x32_bf16 v[14:17], v[22:25], v[72:75], v[14:17]
	ds_read_b128 v[22:25], v70 offset:63808
	v_add_u32_e32 v72, 0x8800, v71
	s_waitcnt lgkmcnt(0)
	v_mfma_f32_16x16x32_bf16 v[18:21], v[26:29], v[22:25], v[18:21]
	ds_read2_b32 v[28:29], v72 offset0:68 offset1:84
	v_mfma_f32_16x16x32_bf16 v[18:21], v[30:33], v[22:25], v[18:21]
	ds_read2_b32 v[22:23], v72 offset1:16
	v_add_u32_e32 v24, s13, v69
	v_ashrrev_i32_e32 v25, 31, v24
	ds_read2_b32 v[30:31], v72 offset0:136 offset1:152
	v_lshlrev_b64 v[26:27], 10, v[24:25]
	s_waitcnt lgkmcnt(1)
	v_add_f32_e32 v10, v10, v22
	v_cvt_pk_bf16_f32 v10, v10, s0
	v_lshl_add_u64 v[26:27], v[56:57], 0, v[26:27]
	ds_read2_b32 v[72:73], v72 offset0:204 offset1:220
	global_store_short v[26:27], v10, off
	v_add_f32_e32 v10, v11, v28
	v_add_u32_e32 v32, 2, v24
	v_cvt_pk_bf16_f32 v22, v10, s0
	v_add_u32_e32 v10, 1, v24
	v_ashrrev_i32_e32 v33, 31, v32
	v_add_f32_e32 v14, v14, v23
	v_ashrrev_i32_e32 v11, 31, v10
	s_waitcnt lgkmcnt(1)
	v_add_f32_e32 v12, v12, v30
	v_lshlrev_b64 v[32:33], 10, v[32:33]
	v_cvt_pk_bf16_f32 v14, v14, s0
	v_lshlrev_b64 v[10:11], 10, v[10:11]
	v_cvt_pk_bf16_f32 v12, v12, s0
	v_lshl_add_u64 v[32:33], v[56:57], 0, v[32:33]
	global_store_short v[26:27], v14, off offset:32
	v_add_f32_e32 v14, v15, v29
	v_lshl_add_u64 v[10:11], v[56:57], 0, v[10:11]
	global_store_short v[32:33], v12, off
	s_waitcnt lgkmcnt(0)
	v_add_f32_e32 v12, v13, v72
	v_cvt_pk_bf16_f32 v14, v14, s0
	global_store_short v[10:11], v22, off
	v_cvt_pk_bf16_f32 v22, v12, s0
	v_add_u32_e32 v12, 3, v24
	global_store_short v[10:11], v14, off offset:32
	v_add_f32_e32 v10, v16, v31
	v_ashrrev_i32_e32 v13, 31, v12
	v_cvt_pk_bf16_f32 v10, v10, s0
	v_lshlrev_b64 v[12:13], 10, v[12:13]
	global_store_short v[32:33], v10, off offset:32
	v_add_f32_e32 v10, v17, v73
	v_lshl_add_u64 v[12:13], v[56:57], 0, v[12:13]
	v_cvt_pk_bf16_f32 v10, v10, s0
	global_store_short v[12:13], v22, off
	global_store_short v[12:13], v10, off offset:32
	s_barrier
	ds_read_b32 v10, v63 offset:17408
	ds_read_b32 v11, v66 offset:17408
	ds_read_b32 v12, v67 offset:17408
	ds_read_b32 v13, v68 offset:17408
	ds_read_b32 v14, v63 offset:17472
	ds_read_b32 v15, v66 offset:17472
	ds_read_b32 v16, v67 offset:17472
	ds_read_b32 v17, v68 offset:17472
	s_add_i32 s13, s13, 64
	s_add_u32 s8, s8, 0x2000
	s_addc_u32 s9, s9, 0
	s_add_i32 s10, s10, 1
	s_cmpk_eq_i32 s13, 0x1000
	s_waitcnt lgkmcnt(0)
	v_add_f32_e32 v10, v34, v10
	v_add_f32_e32 v11, v35, v11
	v_add_f32_e32 v12, v36, v12
	v_add_f32_e32 v13, v37, v13
	v_add_f32_e32 v14, v18, v14
	v_add_f32_e32 v15, v19, v15
	v_add_f32_e32 v16, v20, v16
	v_add_f32_e32 v17, v21, v17
	ds_write_b32 v63, v10
	ds_write_b32 v66, v11
	ds_write_b32 v67, v12
	ds_write_b32 v68, v13
	ds_write_b32 v63, v14 offset:64
	ds_write_b32 v66, v15 offset:64
	ds_write_b32 v67, v16 offset:64
	ds_write_b32 v68, v17 offset:64
	s_cbranch_scc1 .LBB0_624
.LBB0_622:
	s_waitcnt vmcnt(11)
	v_lshlrev_b32_e32 v10, 16, v48
	v_and_b32_e32 v11, 0xffff0000, v48
	v_lshlrev_b32_e32 v12, 16, v49
	v_and_b32_e32 v13, 0xffff0000, v49
	s_waitcnt lgkmcnt(0)
	s_barrier
	ds_write_b128 v39, v[2:5] offset:52224
	ds_write_b128 v39, v[6:9] offset:61440
	ds_write_b128 v45, v[10:13] offset:17408
	s_waitcnt vmcnt(10)
	v_lshlrev_b32_e32 v10, 16, v50
	v_and_b32_e32 v11, 0xffff0000, v50
	v_lshlrev_b32_e32 v12, 16, v51
	v_and_b32_e32 v13, 0xffff0000, v51
	ds_write_b128 v62, v[10:13] offset:17408
	s_waitcnt vmcnt(9)
	v_lshlrev_b32_e32 v10, 16, v52
	v_and_b32_e32 v11, 0xffff0000, v52
	v_lshlrev_b32_e32 v12, 16, v53
	v_and_b32_e32 v13, 0xffff0000, v53
	ds_write_b128 v45, v[10:13] offset:34816
	s_waitcnt vmcnt(8)
	v_lshlrev_b32_e32 v10, 16, v54
	v_and_b32_e32 v11, 0xffff0000, v54
	v_lshlrev_b32_e32 v12, 16, v55
	v_and_b32_e32 v13, 0xffff0000, v55
	s_cmp_gt_u32 s10, 62
	ds_write_b128 v62, v[10:13] offset:34816
	s_waitcnt lgkmcnt(0)
	s_barrier
	s_cbranch_scc1 .LBB0_621
	v_lshl_add_u64 v[2:3], s[8:9], 0, v[42:43]
	v_add_co_u32_e32 v4, vcc, 0x1054a000, v2
	v_lshl_add_u64 v[10:11], s[8:9], 0, v[60:61]
	s_nop 0
	v_addc_co_u32_e32 v5, vcc, 0, v3, vcc
	v_add_co_u32_e32 v6, vcc, 0x1204a000, v2
	v_lshl_add_u64 v[12:13], s[8:9], 0, v[58:59]
	s_nop 0
	v_addc_co_u32_e32 v7, vcc, 0, v3, vcc
	global_load_dwordx4 v[2:5], v[4:5], off
	s_nop 0
	global_load_dwordx4 v[6:9], v[6:7], off
	s_nop 0
	global_load_dwordx2 v[48:49], v[10:11], off
	global_load_dwordx2 v[50:51], v[12:13], off
	v_add_u32_e32 v12, s13, v44
	v_add_u32_e32 v10, 64, v12
	v_ashrrev_i32_e32 v11, 31, v10
	v_add_u32_e32 v12, 0x60, v12
	v_lshlrev_b64 v[10:11], 10, v[10:11]
	v_ashrrev_i32_e32 v13, 31, v12
	v_lshl_add_u64 v[10:11], v[46:47], 0, v[10:11]
	v_lshlrev_b64 v[12:13], 10, v[12:13]
	v_lshl_add_u64 v[12:13], v[46:47], 0, v[12:13]
	global_load_dwordx2 v[52:53], v[10:11], off
	global_load_dwordx2 v[54:55], v[12:13], off
	s_branch .LBB0_621
